# P5 SwiGLU epilogue: hoist the 8 rstd loads to the epilogue head, counted vmcnt(7) instead of vmcnt(0)
# speedup vs baseline: 1.0030x; 1.0030x over previous
.LBB0_1561:
	v_lshl_add_u32 v146, s22, 8, v150
	v_ashrrev_i32_e32 v147, 31, v146
	v_lshl_add_u64 v[148:149], v[146:147], 2, s[8:9]
	global_load_dword v188, v[148:149], off
	global_load_dword v190, v[148:149], off offset:64
	global_load_dword v192, v[148:149], off offset:128
	global_load_dword v194, v[148:149], off offset:192
	global_load_dword v196, v[148:149], off offset:512
	global_load_dword v198, v[148:149], off offset:576
	global_load_dword v200, v[148:149], off offset:640
	global_load_dword v202, v[148:149], off offset:704
	v_lshl_or_b32 v158, s50, 7, v152
	v_mov_b32_e32 v163, v116
	v_mov_b32_e32 v116, v121
	v_mov_b32_e32 v160, v126
	v_mov_b32_e32 v161, v122
	v_mov_b32_e32 v122, v127
	v_mov_b32_e32 v126, v128
	v_mov_b32_e32 v127, v124
	v_mov_b32_e32 v124, v129
	v_mov_b32_e32 v128, v118
	v_mov_b32_e32 v129, v114
	v_mov_b32_e32 v114, v119
	v_mov_b32_e32 v162, v120
	v_mov_b64_e32 v[118:119], s[6:7]
	v_ashrrev_i32_e32 v159, 31, v158
	v_or_b32_e32 v166, 16, v146
	v_mad_i64_i32 v[164:165], s[24:25], v146, s49, v[118:119]
	v_lshlrev_b64 v[120:121], 1, v[158:159]
	v_ashrrev_i32_e32 v167, 31, v166
	v_lshl_add_u64 v[158:159], v[164:165], 0, v[120:121]
	v_lshl_add_u64 v[164:165], v[166:167], 2, s[8:9]
	s_andn2_b64 vcc, exec, s[2:3]
	s_mov_b64 s[2:3], -1
	s_waitcnt vmcnt(7)
	v_pk_mul_f32 v[116:117], v[116:117], v[188:189] op_sel_hi:[1,0]
	v_pk_mul_f32 v[160:161], v[160:161], v[188:189] op_sel_hi:[1,0]
	v_pk_mul_f32 v[122:123], v[122:123], v[188:189] op_sel_hi:[1,0]
	v_pk_mul_f32 v[126:127], v[126:127], v[188:189] op_sel_hi:[1,0]
	v_pk_mul_f32 v[124:125], v[124:125], v[188:189] op_sel_hi:[1,0]
	v_pk_mul_f32 v[128:129], v[128:129], v[188:189] op_sel_hi:[1,0]
	v_pk_mul_f32 v[114:115], v[114:115], v[188:189] op_sel_hi:[1,0]
	v_pk_mul_f32 v[162:163], v[162:163], v[188:189] op_sel_hi:[1,0]
	v_mul_f32_e32 v171, 0xbfb8aa3b, v117
	v_mul_f32_e32 v147, 0xbfb8aa3b, v161
	v_mul_f32_e32 v156, 0xbfb8aa3b, v123
	v_mul_f32_e32 v157, 0xbfb8aa3b, v127
	v_mul_f32_e32 v167, 0xbfb8aa3b, v125
	v_mul_f32_e32 v168, 0xbfb8aa3b, v129
	v_mul_f32_e32 v169, 0xbfb8aa3b, v115
	v_mul_f32_e32 v170, 0xbfb8aa3b, v163
	v_exp_f32_e32 v171, v171
	v_exp_f32_e32 v147, v147
	v_exp_f32_e32 v156, v156
	v_exp_f32_e32 v157, v157
	v_exp_f32_e32 v167, v167
	v_exp_f32_e32 v168, v168
	v_exp_f32_e32 v169, v169
	v_exp_f32_e32 v170, v170
	v_add_f32_e32 v171, 1.0, v171
	v_add_f32_e32 v147, 1.0, v147
	v_add_f32_e32 v156, 1.0, v156
	v_add_f32_e32 v157, 1.0, v157
	v_add_f32_e32 v167, 1.0, v167
	v_add_f32_e32 v168, 1.0, v168
	v_add_f32_e32 v169, 1.0, v169
	v_add_f32_e32 v170, 1.0, v170
	v_rcp_f32_e32 v171, v171
	v_rcp_f32_e32 v147, v147
	v_rcp_f32_e32 v156, v156
	v_rcp_f32_e32 v157, v157
	v_rcp_f32_e32 v167, v167
	v_rcp_f32_e32 v168, v168
	v_rcp_f32_e32 v169, v169
	v_rcp_f32_e32 v170, v170
	v_mul_f32_e32 v117, v117, v171
	v_mul_f32_e32 v147, v161, v147
	v_mul_f32_e32 v123, v123, v156
	v_mul_f32_e32 v127, v127, v157
	v_mul_f32_e32 v125, v125, v167
	v_mul_f32_e32 v129, v129, v168
	v_mul_f32_e32 v115, v115, v169
	v_mul_f32_e32 v156, v163, v170
	v_mul_f32_e32 v117, v116, v117
	v_mul_f32_e32 v147, v160, v147
	v_mul_f32_e32 v122, v122, v123
	v_mul_f32_e32 v123, v126, v127
	v_mul_f32_e32 v124, v124, v125
	v_mul_f32_e32 v125, v128, v129
	v_mul_f32_e32 v126, v114, v115
	v_mul_f32_e32 v127, v162, v156
	v_cvt_pk_bf16_f32 v114, v147, v122
	v_cvt_pk_bf16_f32 v115, v123, v124
	v_cvt_pk_bf16_f32 v116, v125, v126
	v_cvt_pk_bf16_f32 v117, v127, v117
	global_store_dwordx4 v[158:159], v[114:117], off
	s_nop 0
	v_mad_i64_i32 v[122:123], s[24:25], v166, s49, v[118:119]
	v_mov_b32_e32 v117, v106
	v_mov_b32_e32 v106, v111
	v_mov_b32_e32 v111, v108
	v_mov_b32_e32 v108, v113
	v_mov_b32_e32 v113, v98
	v_mov_b32_e32 v98, v103
	v_mov_b32_e32 v103, v100
	v_mov_b32_e32 v100, v105
	v_mov_b32_e32 v116, v110
	v_mov_b32_e32 v110, v112
	v_mov_b32_e32 v112, v102
	v_mov_b32_e32 v102, v104
	v_or_b32_e32 v104, 32, v146
	v_ashrrev_i32_e32 v105, 31, v104
	v_lshl_add_u64 v[124:125], v[104:105], 2, s[8:9]
	v_lshl_add_u64 v[122:123], v[122:123], 0, v[120:121]
	s_waitcnt vmcnt(7)
	v_pk_mul_f32 v[100:101], v[100:101], v[190:191] op_sel_hi:[1,0]
	v_pk_mul_f32 v[116:117], v[116:117], v[190:191] op_sel_hi:[1,0]
	v_pk_mul_f32 v[106:107], v[106:107], v[190:191] op_sel_hi:[1,0]
	v_pk_mul_f32 v[110:111], v[110:111], v[190:191] op_sel_hi:[1,0]
	v_pk_mul_f32 v[108:109], v[108:109], v[190:191] op_sel_hi:[1,0]
	v_pk_mul_f32 v[112:113], v[112:113], v[190:191] op_sel_hi:[1,0]
	v_pk_mul_f32 v[98:99], v[98:99], v[190:191] op_sel_hi:[1,0]
	v_pk_mul_f32 v[102:103], v[102:103], v[190:191] op_sel_hi:[1,0]
	v_mul_f32_e32 v147, 0xbfb8aa3b, v101
	v_mul_f32_e32 v105, 0xbfb8aa3b, v117
	v_mul_f32_e32 v114, 0xbfb8aa3b, v107
	v_mul_f32_e32 v115, 0xbfb8aa3b, v111
	v_mul_f32_e32 v126, 0xbfb8aa3b, v109
	v_mul_f32_e32 v127, 0xbfb8aa3b, v113
	v_mul_f32_e32 v128, 0xbfb8aa3b, v99
	v_mul_f32_e32 v129, 0xbfb8aa3b, v103
	v_exp_f32_e32 v147, v147
	v_exp_f32_e32 v105, v105
	v_exp_f32_e32 v114, v114
	v_exp_f32_e32 v115, v115
	v_exp_f32_e32 v126, v126
	v_exp_f32_e32 v127, v127
	v_exp_f32_e32 v128, v128
	v_exp_f32_e32 v129, v129
	v_add_f32_e32 v147, 1.0, v147
	v_add_f32_e32 v105, 1.0, v105
	v_add_f32_e32 v114, 1.0, v114
	v_add_f32_e32 v115, 1.0, v115
	v_add_f32_e32 v126, 1.0, v126
	v_add_f32_e32 v127, 1.0, v127
	v_add_f32_e32 v128, 1.0, v128
	v_add_f32_e32 v129, 1.0, v129
	v_rcp_f32_e32 v147, v147
	v_rcp_f32_e32 v105, v105
	v_rcp_f32_e32 v114, v114
	v_rcp_f32_e32 v115, v115
	v_rcp_f32_e32 v126, v126
	v_rcp_f32_e32 v127, v127
	v_rcp_f32_e32 v128, v128
	v_rcp_f32_e32 v129, v129
	v_mul_f32_e32 v101, v101, v147
	v_mul_f32_e32 v105, v117, v105
	v_mul_f32_e32 v107, v107, v114
	v_mul_f32_e32 v111, v111, v115
	v_mul_f32_e32 v109, v109, v126
	v_mul_f32_e32 v113, v113, v127
	v_mul_f32_e32 v99, v99, v128
	v_mul_f32_e32 v103, v103, v129
	v_mul_f32_e32 v101, v100, v101
	v_mul_f32_e32 v105, v116, v105
	v_mul_f32_e32 v106, v106, v107
	v_mul_f32_e32 v107, v110, v111
	v_mul_f32_e32 v108, v108, v109
	v_mul_f32_e32 v109, v112, v113
	v_mul_f32_e32 v110, v98, v99
	v_mul_f32_e32 v102, v102, v103
	v_cvt_pk_bf16_f32 v98, v105, v106
	v_cvt_pk_bf16_f32 v99, v107, v108
	v_cvt_pk_bf16_f32 v100, v109, v110
	v_cvt_pk_bf16_f32 v101, v102, v101
	global_store_dwordx4 v[122:123], v[98:101], off
	s_nop 0
	v_mad_i64_i32 v[102:103], s[24:25], v104, s49, v[118:119]
	v_mov_b32_e32 v101, v90
	v_mov_b32_e32 v90, v95
	v_mov_b32_e32 v95, v92
	v_mov_b32_e32 v92, v97
	v_mov_b32_e32 v97, v82
	v_mov_b32_e32 v82, v87
	v_mov_b32_e32 v87, v84
	v_mov_b32_e32 v84, v89
	v_mov_b32_e32 v100, v94
	v_mov_b32_e32 v94, v96
	v_mov_b32_e32 v96, v86
	v_mov_b32_e32 v86, v88
	v_or_b32_e32 v88, 48, v146
	v_ashrrev_i32_e32 v89, 31, v88
	v_lshl_add_u64 v[104:105], v[88:89], 2, s[8:9]
	v_lshl_add_u64 v[102:103], v[102:103], 0, v[120:121]
	s_waitcnt vmcnt(7)
	v_pk_mul_f32 v[84:85], v[84:85], v[192:193] op_sel_hi:[1,0]
	v_pk_mul_f32 v[100:101], v[100:101], v[192:193] op_sel_hi:[1,0]
	v_pk_mul_f32 v[90:91], v[90:91], v[192:193] op_sel_hi:[1,0]
	v_pk_mul_f32 v[94:95], v[94:95], v[192:193] op_sel_hi:[1,0]
	v_pk_mul_f32 v[92:93], v[92:93], v[192:193] op_sel_hi:[1,0]
	v_pk_mul_f32 v[96:97], v[96:97], v[192:193] op_sel_hi:[1,0]
	v_pk_mul_f32 v[82:83], v[82:83], v[192:193] op_sel_hi:[1,0]
	v_pk_mul_f32 v[86:87], v[86:87], v[192:193] op_sel_hi:[1,0]
	v_mul_f32_e32 v110, 0xbfb8aa3b, v85
	v_mul_f32_e32 v89, 0xbfb8aa3b, v101
	v_mul_f32_e32 v98, 0xbfb8aa3b, v91
	v_mul_f32_e32 v99, 0xbfb8aa3b, v95
	v_mul_f32_e32 v106, 0xbfb8aa3b, v93
	v_mul_f32_e32 v107, 0xbfb8aa3b, v97
	v_mul_f32_e32 v108, 0xbfb8aa3b, v83
	v_mul_f32_e32 v109, 0xbfb8aa3b, v87
	v_exp_f32_e32 v110, v110
	v_exp_f32_e32 v89, v89
	v_exp_f32_e32 v98, v98
	v_exp_f32_e32 v99, v99
	v_exp_f32_e32 v106, v106
	v_exp_f32_e32 v107, v107
	v_exp_f32_e32 v108, v108
	v_exp_f32_e32 v109, v109
	v_add_f32_e32 v110, 1.0, v110
	v_add_f32_e32 v89, 1.0, v89
	v_add_f32_e32 v98, 1.0, v98
	v_add_f32_e32 v99, 1.0, v99
	v_add_f32_e32 v106, 1.0, v106
	v_add_f32_e32 v107, 1.0, v107
	v_add_f32_e32 v108, 1.0, v108
	v_add_f32_e32 v109, 1.0, v109
	v_rcp_f32_e32 v110, v110
	v_rcp_f32_e32 v89, v89
	v_rcp_f32_e32 v98, v98
	v_rcp_f32_e32 v99, v99
	v_rcp_f32_e32 v106, v106
	v_rcp_f32_e32 v107, v107
	v_rcp_f32_e32 v108, v108
	v_rcp_f32_e32 v109, v109
	v_mul_f32_e32 v85, v85, v110
	v_mul_f32_e32 v89, v101, v89
	v_mul_f32_e32 v91, v91, v98
	v_mul_f32_e32 v95, v95, v99
	v_mul_f32_e32 v93, v93, v106
	v_mul_f32_e32 v97, v97, v107
	v_mul_f32_e32 v83, v83, v108
	v_mul_f32_e32 v87, v87, v109
	v_mul_f32_e32 v85, v84, v85
	v_mul_f32_e32 v89, v100, v89
	v_mul_f32_e32 v90, v90, v91
	v_mul_f32_e32 v91, v94, v95
	v_mul_f32_e32 v92, v92, v93
	v_mul_f32_e32 v93, v96, v97
	v_mul_f32_e32 v94, v82, v83
	v_mul_f32_e32 v86, v86, v87
	v_cvt_pk_bf16_f32 v82, v89, v90
	v_cvt_pk_bf16_f32 v83, v91, v92
	v_cvt_pk_bf16_f32 v84, v93, v94
	v_cvt_pk_bf16_f32 v85, v86, v85
	global_store_dwordx4 v[102:103], v[82:85], off
	s_nop 0
	s_nop 0
	v_mov_b32_e32 v84, v78
	v_mov_b32_e32 v85, v74
	v_mov_b32_e32 v74, v79
	v_mov_b32_e32 v78, v80
	v_mov_b32_e32 v79, v76
	v_mov_b32_e32 v76, v81
	v_mov_b32_e32 v80, v66
	v_mov_b32_e32 v81, v70
	v_mov_b32_e32 v70, v67
	v_mov_b32_e32 v66, v68
	v_mov_b32_e32 v67, v72
	v_mov_b32_e32 v72, v69
	v_mad_i64_i32 v[68:69], s[24:25], v88, s49, v[118:119]
	v_lshl_add_u64 v[86:87], v[68:69], 0, v[120:121]
	s_waitcnt vmcnt(7)
	v_pk_mul_f32 v[68:69], v[84:85], v[194:195] op_sel_hi:[1,0]
	v_pk_mul_f32 v[74:75], v[74:75], v[194:195] op_sel_hi:[1,0]
	v_pk_mul_f32 v[78:79], v[78:79], v[194:195] op_sel_hi:[1,0]
	v_pk_mul_f32 v[76:77], v[76:77], v[194:195] op_sel_hi:[1,0]
	v_pk_mul_f32 v[80:81], v[80:81], v[194:195] op_sel_hi:[1,0]
	v_pk_mul_f32 v[70:71], v[70:71], v[194:195] op_sel_hi:[1,0]
	v_pk_mul_f32 v[66:67], v[66:67], v[194:195] op_sel_hi:[1,0]
	v_pk_mul_f32 v[72:73], v[72:73], v[194:195] op_sel_hi:[1,0]
	v_mul_f32_e32 v82, 0xbfb8aa3b, v69
	v_mul_f32_e32 v83, 0xbfb8aa3b, v75
	v_mul_f32_e32 v84, 0xbfb8aa3b, v79
	v_mul_f32_e32 v85, 0xbfb8aa3b, v77
	v_mul_f32_e32 v88, 0xbfb8aa3b, v81
	v_mul_f32_e32 v89, 0xbfb8aa3b, v71
	v_mul_f32_e32 v90, 0xbfb8aa3b, v67
	v_mul_f32_e32 v91, 0xbfb8aa3b, v73
	v_exp_f32_e32 v82, v82
	v_exp_f32_e32 v83, v83
	v_exp_f32_e32 v84, v84
	v_exp_f32_e32 v85, v85
	v_exp_f32_e32 v88, v88
	v_exp_f32_e32 v89, v89
	v_exp_f32_e32 v90, v90
	v_exp_f32_e32 v91, v91
	v_add_f32_e32 v82, 1.0, v82
	v_add_f32_e32 v83, 1.0, v83
	v_add_f32_e32 v84, 1.0, v84
	v_add_f32_e32 v85, 1.0, v85
	v_add_f32_e32 v88, 1.0, v88
	v_add_f32_e32 v89, 1.0, v89
	v_add_f32_e32 v90, 1.0, v90
	v_add_f32_e32 v91, 1.0, v91
	v_rcp_f32_e32 v82, v82
	v_rcp_f32_e32 v83, v83
	v_rcp_f32_e32 v84, v84
	v_rcp_f32_e32 v85, v85
	v_rcp_f32_e32 v88, v88
	v_rcp_f32_e32 v89, v89
	v_rcp_f32_e32 v90, v90
	v_rcp_f32_e32 v91, v91
	v_mul_f32_e32 v69, v69, v82
	v_mul_f32_e32 v75, v75, v83
	v_mul_f32_e32 v79, v79, v84
	v_mul_f32_e32 v77, v77, v85
	v_mul_f32_e32 v81, v81, v88
	v_mul_f32_e32 v71, v71, v89
	v_mul_f32_e32 v67, v67, v90
	v_mul_f32_e32 v73, v73, v91
	v_mul_f32_e32 v68, v68, v69
	v_mul_f32_e32 v69, v74, v75
	v_mul_f32_e32 v74, v78, v79
	v_mul_f32_e32 v75, v76, v77
	v_mul_f32_e32 v76, v80, v81
	v_mul_f32_e32 v70, v70, v71
	v_mul_f32_e32 v71, v66, v67
	v_mul_f32_e32 v72, v72, v73
	v_cvt_pk_bf16_f32 v66, v68, v69
	v_cvt_pk_bf16_f32 v67, v74, v75
	v_cvt_pk_bf16_f32 v68, v76, v70
	v_cvt_pk_bf16_f32 v69, v71, v72
	global_store_dwordx4 v[86:87], v[66:69], off
	s_nop 0
	s_nop 0
	v_mov_b32_e32 v68, v62
	v_mov_b32_e32 v62, v64
	v_mov_b32_e32 v64, v50
	v_mov_b32_e32 v50, v52
	v_add_u32_e32 v52, 0x80, v146
	v_mov_b32_e32 v69, v58
	v_mov_b32_e32 v58, v63
	v_mov_b32_e32 v63, v60
	v_mov_b32_e32 v60, v65
	v_mov_b32_e32 v65, v54
	v_mov_b32_e32 v54, v51
	v_mov_b32_e32 v51, v56
	v_mov_b32_e32 v56, v53
	v_mad_i64_i32 v[52:53], s[24:25], v52, s49, v[118:119]
	v_lshl_add_u64 v[70:71], v[52:53], 0, v[120:121]
	s_waitcnt vmcnt(7)
	v_pk_mul_f32 v[52:53], v[68:69], v[196:197] op_sel_hi:[1,0]
	v_pk_mul_f32 v[58:59], v[58:59], v[196:197] op_sel_hi:[1,0]
	v_pk_mul_f32 v[62:63], v[62:63], v[196:197] op_sel_hi:[1,0]
	v_pk_mul_f32 v[60:61], v[60:61], v[196:197] op_sel_hi:[1,0]
	v_pk_mul_f32 v[64:65], v[64:65], v[196:197] op_sel_hi:[1,0]
	v_pk_mul_f32 v[54:55], v[54:55], v[196:197] op_sel_hi:[1,0]
	v_pk_mul_f32 v[50:51], v[50:51], v[196:197] op_sel_hi:[1,0]
	v_pk_mul_f32 v[56:57], v[56:57], v[196:197] op_sel_hi:[1,0]
	v_mul_f32_e32 v66, 0xbfb8aa3b, v53
	v_mul_f32_e32 v67, 0xbfb8aa3b, v59
	v_mul_f32_e32 v68, 0xbfb8aa3b, v63
	v_mul_f32_e32 v69, 0xbfb8aa3b, v61
	v_mul_f32_e32 v72, 0xbfb8aa3b, v65
	v_mul_f32_e32 v73, 0xbfb8aa3b, v55
	v_mul_f32_e32 v74, 0xbfb8aa3b, v51
	v_mul_f32_e32 v75, 0xbfb8aa3b, v57
	v_exp_f32_e32 v66, v66
	v_exp_f32_e32 v67, v67
	v_exp_f32_e32 v68, v68
	v_exp_f32_e32 v69, v69
	v_exp_f32_e32 v72, v72
	v_exp_f32_e32 v73, v73
	v_exp_f32_e32 v74, v74
	v_exp_f32_e32 v75, v75
	v_add_f32_e32 v66, 1.0, v66
	v_add_f32_e32 v67, 1.0, v67
	v_add_f32_e32 v68, 1.0, v68
	v_add_f32_e32 v69, 1.0, v69
	v_add_f32_e32 v72, 1.0, v72
	v_add_f32_e32 v73, 1.0, v73
	v_add_f32_e32 v74, 1.0, v74
	v_add_f32_e32 v75, 1.0, v75
	v_rcp_f32_e32 v66, v66
	v_rcp_f32_e32 v67, v67
	v_rcp_f32_e32 v68, v68
	v_rcp_f32_e32 v69, v69
	v_rcp_f32_e32 v72, v72
	v_rcp_f32_e32 v73, v73
	v_rcp_f32_e32 v74, v74
	v_rcp_f32_e32 v75, v75
	v_mul_f32_e32 v53, v53, v66
	v_mul_f32_e32 v59, v59, v67
	v_mul_f32_e32 v63, v63, v68
	v_mul_f32_e32 v61, v61, v69
	v_mul_f32_e32 v65, v65, v72
	v_mul_f32_e32 v55, v55, v73
	v_mul_f32_e32 v51, v51, v74
	v_mul_f32_e32 v57, v57, v75
	v_mul_f32_e32 v52, v52, v53
	v_mul_f32_e32 v53, v58, v59
	v_mul_f32_e32 v58, v62, v63
	v_mul_f32_e32 v59, v60, v61
	v_mul_f32_e32 v60, v64, v65
	v_mul_f32_e32 v54, v54, v55
	v_mul_f32_e32 v55, v50, v51
	v_mul_f32_e32 v56, v56, v57
	v_cvt_pk_bf16_f32 v50, v52, v53
	v_cvt_pk_bf16_f32 v51, v58, v59
	v_cvt_pk_bf16_f32 v52, v60, v54
	v_cvt_pk_bf16_f32 v53, v55, v56
	global_store_dwordx4 v[70:71], v[50:53], off
	s_nop 0
	s_nop 0
	v_mov_b32_e32 v52, v46
	v_mov_b32_e32 v46, v48
	v_mov_b32_e32 v48, v34
	v_mov_b32_e32 v34, v36
	v_add_u32_e32 v36, 0x90, v146
	v_mov_b32_e32 v53, v42
	v_mov_b32_e32 v42, v47
	v_mov_b32_e32 v47, v44
	v_mov_b32_e32 v44, v49
	v_mov_b32_e32 v49, v38
	v_mov_b32_e32 v38, v35
	v_mov_b32_e32 v35, v40
	v_mov_b32_e32 v40, v37
	v_mad_i64_i32 v[36:37], s[24:25], v36, s49, v[118:119]
	v_lshl_add_u64 v[54:55], v[36:37], 0, v[120:121]
	s_waitcnt vmcnt(7)
	v_pk_mul_f32 v[36:37], v[52:53], v[198:199] op_sel_hi:[1,0]
	v_pk_mul_f32 v[42:43], v[42:43], v[198:199] op_sel_hi:[1,0]
	v_pk_mul_f32 v[46:47], v[46:47], v[198:199] op_sel_hi:[1,0]
	v_pk_mul_f32 v[44:45], v[44:45], v[198:199] op_sel_hi:[1,0]
	v_pk_mul_f32 v[48:49], v[48:49], v[198:199] op_sel_hi:[1,0]
	v_pk_mul_f32 v[38:39], v[38:39], v[198:199] op_sel_hi:[1,0]
	v_pk_mul_f32 v[34:35], v[34:35], v[198:199] op_sel_hi:[1,0]
	v_pk_mul_f32 v[40:41], v[40:41], v[198:199] op_sel_hi:[1,0]
	v_mul_f32_e32 v50, 0xbfb8aa3b, v37
	v_mul_f32_e32 v51, 0xbfb8aa3b, v43
	v_mul_f32_e32 v52, 0xbfb8aa3b, v47
	v_mul_f32_e32 v53, 0xbfb8aa3b, v45
	v_mul_f32_e32 v56, 0xbfb8aa3b, v49
	v_mul_f32_e32 v57, 0xbfb8aa3b, v39
	v_mul_f32_e32 v58, 0xbfb8aa3b, v35
	v_mul_f32_e32 v59, 0xbfb8aa3b, v41
	v_exp_f32_e32 v50, v50
	v_exp_f32_e32 v51, v51
	v_exp_f32_e32 v52, v52
	v_exp_f32_e32 v53, v53
	v_exp_f32_e32 v56, v56
	v_exp_f32_e32 v57, v57
	v_exp_f32_e32 v58, v58
	v_exp_f32_e32 v59, v59
	v_add_f32_e32 v50, 1.0, v50
	v_add_f32_e32 v51, 1.0, v51
	v_add_f32_e32 v52, 1.0, v52
	v_add_f32_e32 v53, 1.0, v53
	v_add_f32_e32 v56, 1.0, v56
	v_add_f32_e32 v57, 1.0, v57
	v_add_f32_e32 v58, 1.0, v58
	v_add_f32_e32 v59, 1.0, v59
	v_rcp_f32_e32 v50, v50
	v_rcp_f32_e32 v51, v51
	v_rcp_f32_e32 v52, v52
	v_rcp_f32_e32 v53, v53
	v_rcp_f32_e32 v56, v56
	v_rcp_f32_e32 v57, v57
	v_rcp_f32_e32 v58, v58
	v_rcp_f32_e32 v59, v59
	v_mul_f32_e32 v37, v37, v50
	v_mul_f32_e32 v43, v43, v51
	v_mul_f32_e32 v47, v47, v52
	v_mul_f32_e32 v45, v45, v53
	v_mul_f32_e32 v49, v49, v56
	v_mul_f32_e32 v39, v39, v57
	v_mul_f32_e32 v35, v35, v58
	v_mul_f32_e32 v41, v41, v59
	v_mul_f32_e32 v36, v36, v37
	v_mul_f32_e32 v37, v42, v43
	v_mul_f32_e32 v42, v46, v47
	v_mul_f32_e32 v43, v44, v45
	v_mul_f32_e32 v44, v48, v49
	v_mul_f32_e32 v38, v38, v39
	v_mul_f32_e32 v39, v34, v35
	v_mul_f32_e32 v40, v40, v41
	v_cvt_pk_bf16_f32 v34, v36, v37
	v_cvt_pk_bf16_f32 v35, v42, v43
	v_cvt_pk_bf16_f32 v36, v44, v38
	v_cvt_pk_bf16_f32 v37, v39, v40
	global_store_dwordx4 v[54:55], v[34:37], off
	s_nop 0
	s_nop 0
	v_mov_b32_e32 v36, v30
	v_mov_b32_e32 v30, v32
	v_mov_b32_e32 v32, v18
	v_mov_b32_e32 v18, v20
	v_add_u32_e32 v20, 0xa0, v146
	v_mov_b32_e32 v37, v26
	v_mov_b32_e32 v26, v31
	v_mov_b32_e32 v31, v28
	v_mov_b32_e32 v28, v33
	v_mov_b32_e32 v33, v22
	v_mov_b32_e32 v22, v19
	v_mov_b32_e32 v19, v24
	v_mov_b32_e32 v24, v21
	v_mad_i64_i32 v[20:21], s[24:25], v20, s49, v[118:119]
	v_lshl_add_u64 v[38:39], v[20:21], 0, v[120:121]
	s_waitcnt vmcnt(7)
	v_pk_mul_f32 v[20:21], v[36:37], v[200:201] op_sel_hi:[1,0]
	v_pk_mul_f32 v[26:27], v[26:27], v[200:201] op_sel_hi:[1,0]
	v_pk_mul_f32 v[30:31], v[30:31], v[200:201] op_sel_hi:[1,0]
	v_pk_mul_f32 v[28:29], v[28:29], v[200:201] op_sel_hi:[1,0]
	v_pk_mul_f32 v[32:33], v[32:33], v[200:201] op_sel_hi:[1,0]
	v_pk_mul_f32 v[22:23], v[22:23], v[200:201] op_sel_hi:[1,0]
	v_pk_mul_f32 v[18:19], v[18:19], v[200:201] op_sel_hi:[1,0]
	v_pk_mul_f32 v[24:25], v[24:25], v[200:201] op_sel_hi:[1,0]
	v_mul_f32_e32 v34, 0xbfb8aa3b, v21
	v_mul_f32_e32 v35, 0xbfb8aa3b, v27
	v_mul_f32_e32 v36, 0xbfb8aa3b, v31
	v_mul_f32_e32 v37, 0xbfb8aa3b, v29
	v_mul_f32_e32 v40, 0xbfb8aa3b, v33
	v_mul_f32_e32 v41, 0xbfb8aa3b, v23
	v_mul_f32_e32 v42, 0xbfb8aa3b, v19
	v_mul_f32_e32 v43, 0xbfb8aa3b, v25
	v_exp_f32_e32 v34, v34
	v_exp_f32_e32 v35, v35
	v_exp_f32_e32 v36, v36
	v_exp_f32_e32 v37, v37
	v_exp_f32_e32 v40, v40
	v_exp_f32_e32 v41, v41
	v_exp_f32_e32 v42, v42
	v_exp_f32_e32 v43, v43
	v_add_f32_e32 v34, 1.0, v34
	v_add_f32_e32 v35, 1.0, v35
	v_add_f32_e32 v36, 1.0, v36
	v_add_f32_e32 v37, 1.0, v37
	v_add_f32_e32 v40, 1.0, v40
	v_add_f32_e32 v41, 1.0, v41
	v_add_f32_e32 v42, 1.0, v42
	v_add_f32_e32 v43, 1.0, v43
	v_rcp_f32_e32 v34, v34
	v_rcp_f32_e32 v35, v35
	v_rcp_f32_e32 v36, v36
	v_rcp_f32_e32 v37, v37
	v_rcp_f32_e32 v40, v40
	v_rcp_f32_e32 v41, v41
	v_rcp_f32_e32 v42, v42
	v_rcp_f32_e32 v43, v43
	v_mul_f32_e32 v21, v21, v34
	v_mul_f32_e32 v27, v27, v35
	v_mul_f32_e32 v31, v31, v36
	v_mul_f32_e32 v29, v29, v37
	v_mul_f32_e32 v33, v33, v40
	v_mul_f32_e32 v23, v23, v41
	v_mul_f32_e32 v19, v19, v42
	v_mul_f32_e32 v25, v25, v43
	v_mul_f32_e32 v20, v20, v21
	v_mul_f32_e32 v21, v26, v27
	v_mul_f32_e32 v26, v30, v31
	v_mul_f32_e32 v27, v28, v29
	v_mul_f32_e32 v28, v32, v33
	v_mul_f32_e32 v22, v22, v23
	v_mul_f32_e32 v23, v18, v19
	v_mul_f32_e32 v24, v24, v25
	v_cvt_pk_bf16_f32 v18, v20, v21
	v_cvt_pk_bf16_f32 v19, v26, v27
	v_cvt_pk_bf16_f32 v20, v28, v22
	v_cvt_pk_bf16_f32 v21, v23, v24
	global_store_dwordx4 v[38:39], v[18:21], off
	s_nop 0
	s_nop 0
	v_mov_b32_e32 v20, v14
	v_mov_b32_e32 v14, v16
	v_mov_b32_e32 v16, v2
	v_mov_b32_e32 v2, v4
	v_add_u32_e32 v4, 0xb0, v146
	v_mov_b32_e32 v21, v10
	v_mov_b32_e32 v10, v15
	v_mov_b32_e32 v15, v12
	v_mov_b32_e32 v12, v17
	v_mov_b32_e32 v17, v6
	v_mov_b32_e32 v6, v3
	v_mov_b32_e32 v3, v8
	v_mov_b32_e32 v8, v5
	v_mad_i64_i32 v[4:5], s[24:25], v4, s49, v[118:119]
	v_lshl_add_u64 v[22:23], v[4:5], 0, v[120:121]
	s_waitcnt vmcnt(7)
	v_pk_mul_f32 v[4:5], v[20:21], v[202:203] op_sel_hi:[1,0]
	v_pk_mul_f32 v[10:11], v[10:11], v[202:203] op_sel_hi:[1,0]
	v_pk_mul_f32 v[14:15], v[14:15], v[202:203] op_sel_hi:[1,0]
	v_pk_mul_f32 v[12:13], v[12:13], v[202:203] op_sel_hi:[1,0]
	v_pk_mul_f32 v[16:17], v[16:17], v[202:203] op_sel_hi:[1,0]
	v_pk_mul_f32 v[6:7], v[6:7], v[202:203] op_sel_hi:[1,0]
	v_pk_mul_f32 v[2:3], v[2:3], v[202:203] op_sel_hi:[1,0]
	v_pk_mul_f32 v[8:9], v[8:9], v[202:203] op_sel_hi:[1,0]
	v_mul_f32_e32 v18, 0xbfb8aa3b, v5
	v_mul_f32_e32 v19, 0xbfb8aa3b, v11
	v_mul_f32_e32 v20, 0xbfb8aa3b, v15
	v_mul_f32_e32 v21, 0xbfb8aa3b, v13
	v_mul_f32_e32 v24, 0xbfb8aa3b, v17
	v_mul_f32_e32 v25, 0xbfb8aa3b, v7
	v_mul_f32_e32 v26, 0xbfb8aa3b, v3
	v_mul_f32_e32 v27, 0xbfb8aa3b, v9
	v_exp_f32_e32 v18, v18
	v_exp_f32_e32 v19, v19
	v_exp_f32_e32 v20, v20
	v_exp_f32_e32 v21, v21
	v_exp_f32_e32 v24, v24
	v_exp_f32_e32 v25, v25
	v_exp_f32_e32 v26, v26
	v_exp_f32_e32 v27, v27
	v_add_f32_e32 v18, 1.0, v18
	v_add_f32_e32 v19, 1.0, v19
	v_add_f32_e32 v20, 1.0, v20
	v_add_f32_e32 v21, 1.0, v21
	v_add_f32_e32 v24, 1.0, v24
	v_add_f32_e32 v25, 1.0, v25
	v_add_f32_e32 v26, 1.0, v26
	v_add_f32_e32 v27, 1.0, v27
	v_rcp_f32_e32 v18, v18
	v_rcp_f32_e32 v19, v19
	v_rcp_f32_e32 v20, v20
	v_rcp_f32_e32 v21, v21
	v_rcp_f32_e32 v24, v24
	v_rcp_f32_e32 v25, v25
	v_rcp_f32_e32 v26, v26
	v_rcp_f32_e32 v27, v27
	v_mul_f32_e32 v5, v5, v18
	v_mul_f32_e32 v11, v11, v19
	v_mul_f32_e32 v15, v15, v20
	v_mul_f32_e32 v13, v13, v21
	v_mul_f32_e32 v17, v17, v24
	v_mul_f32_e32 v7, v7, v25
	v_mul_f32_e32 v3, v3, v26
	v_mul_f32_e32 v9, v9, v27
	v_mul_f32_e32 v4, v4, v5
	v_mul_f32_e32 v5, v10, v11
	v_mul_f32_e32 v10, v14, v15
	v_mul_f32_e32 v11, v12, v13
	v_mul_f32_e32 v12, v16, v17
	v_mul_f32_e32 v6, v6, v7
	v_mul_f32_e32 v7, v2, v3
	v_mul_f32_e32 v8, v8, v9
	v_cvt_pk_bf16_f32 v2, v4, v5
	v_cvt_pk_bf16_f32 v3, v10, v11
	v_cvt_pk_bf16_f32 v4, v12, v6
	v_cvt_pk_bf16_f32 v5, v7, v8
	global_store_dwordx4 v[22:23], v[2:5], off
	s_cbranch_vccnz .LBB0_1554
	s_andn2_b64 vcc, exec, s[4:5]
	s_cbranch_vccnz .LBB0_1553
	s_barrier
	s_branch .LBB0_1553
